# LayerNorm row loops: 64-lane sums via DPP row_shr/row_bcast adds + readlane broadcast instead of six ds_bpermute round trips each
# baseline (speedup 1.0000x reference)
; DI unsigned pk2(float lo, float hi) { const hwf2_t v = {lo, hi}; const hwbf2_t b = __builtin_convertvector(v, hwbf2_t); return __builtin_bit_cast(unsigned, b); }
; DI float lo16(unsigned w) { return __uint_as_float(w << 16); }
; DI float hi16(unsigned w) { return __uint_as_float(w & 0xffff0000u); }
; DI float wave_sum(float v) { for (int o = 32; o >= 1; o >>= 1) v += __shfl_xor(v, o); return v; }
; DI void ln_pass(CP c, int mode, const float* gam, const float* bet, const float* modsc, const float* modsh, int bid, int nb, bool fin) {
;     ...
;     for (int r = bid * 8 + wave; r < MT; r += nb * 8) {
;         f32x4 v[4];
;         if (mode == 0) { const float* src = r < MP ? c->in[I_XP] + (size_t)r * DM : c->in[I_XS] + (size_t)(r - MP) * DM;
; #pragma unroll
;             for (int i = 0; i < 4; ++i) v[i] = *(const f32x4*)(src + lane * 4 + 256 * i); }
;         else {
; #pragma unroll
;             for (int i = 0; i < 4; ++i) { const u32x2 w = *(const u32x2*)(XB + (size_t)r * DM + lane * 4 + 256 * i); v[i] = (f32x4){lo16(w.x), hi16(w.x), lo16(w.y), hi16(w.y)}; } }
;         if (mode != 1) {
;             float s = 0.f;
; #pragma unroll
;             for (int i = 0; i < 4; ++i) s += v[i][0] + v[i][1] + v[i][2] + v[i][3];
;             const float mean = wave_sum(s) * (1.f / 1024.f); float q = 0.f;
; #pragma unroll
;             for (int i = 0; i < 4; ++i) { const f32x4 d = v[i] - mean; q += d[0] * d[0] + d[1] * d[1] + d[2] * d[2] + d[3] * d[3]; }
;             const float rstd = rsqrtf(wave_sum(q) * (1.f / 1024.f) + 1e-5f);
; #pragma unroll
;             for (int i = 0; i < 4; ++i) { const int col = lane * 4 + 256 * i; const f32x4 g = *(const f32x4*)(gam + col), b = *(const f32x4*)(bet + col);
;                 v[i] = (v[i] - mean) * rstd * g + b;
;                 if (fin) *(f32x4*)(c->out + (size_t)r * DM + col) = v[i];
;                 else { u32x2 w; w.x = pk2(v[i][0], v[i][1]); w.y = pk2(v[i][2], v[i][3]); *(u32x2*)(XB + (size_t)r * DM + col) = w; } }
.Lln0_nopf_a:
	s_waitcnt vmcnt(4)
	v_add_f32_e32 v0, v92, v93
	v_add_f32_e32 v0, v0, v94
	v_add_f32_e32 v0, v0, v95
	v_add_f32_e32 v0, v0, v96
	v_add_f32_e32 v0, v0, v97
	v_add_f32_e32 v0, v0, v98
	v_add_f32_e32 v0, v0, v99
	v_add_f32_e32 v0, v0, v100
	v_add_f32_e32 v0, v0, v101
	v_add_f32_e32 v0, v0, v102
	v_add_f32_e32 v0, v0, v103
	v_add_f32_e32 v0, v0, v104
	v_add_f32_e32 v0, v0, v105
	v_add_f32_e32 v0, v0, v106
	v_add_f32_e32 v0, v0, v107
	s_nop 1
	v_add_f32_dpp v0, v0, v0 row_shr:1 row_mask:0xf bank_mask:0xf bound_ctrl:0
	s_nop 1
	v_add_f32_dpp v0, v0, v0 row_shr:2 row_mask:0xf bank_mask:0xf bound_ctrl:0
	s_nop 1
	v_add_f32_dpp v0, v0, v0 row_shr:4 row_mask:0xf bank_mask:0xf bound_ctrl:0
	s_nop 1
	v_add_f32_dpp v0, v0, v0 row_shr:8 row_mask:0xf bank_mask:0xf bound_ctrl:0
	s_nop 1
	v_add_f32_dpp v0, v0, v0 row_bcast:15 row_mask:0xa bank_mask:0xf
	s_nop 1
	v_add_f32_dpp v0, v0, v0 row_bcast:31 row_mask:0xc bank_mask:0xf
	s_nop 1
	v_readlane_b32 vcc_lo, v0, 63
	s_nop 1
	v_mov_b32_e32 v0, vcc_lo
	v_fmac_f32_e32 v92, 0xba800000, v0
	v_fmac_f32_e32 v93, 0xba800000, v0
	v_fmac_f32_e32 v94, 0xba800000, v0
	v_fmac_f32_e32 v95, 0xba800000, v0
	v_fmac_f32_e32 v96, 0xba800000, v0
	v_fmac_f32_e32 v97, 0xba800000, v0
	v_fmac_f32_e32 v98, 0xba800000, v0
	v_fmac_f32_e32 v99, 0xba800000, v0
	v_fmac_f32_e32 v100, 0xba800000, v0
	v_fmac_f32_e32 v101, 0xba800000, v0
	v_fmac_f32_e32 v102, 0xba800000, v0
	v_fmac_f32_e32 v103, 0xba800000, v0
	v_fmac_f32_e32 v104, 0xba800000, v0
	v_fmac_f32_e32 v105, 0xba800000, v0
	v_fmac_f32_e32 v106, 0xba800000, v0
	v_fmac_f32_e32 v107, 0xba800000, v0
	v_mul_f32_e32 v55, v92, v92
	v_fmac_f32_e32 v55, v93, v93
	v_fmac_f32_e32 v55, v94, v94
	v_fmac_f32_e32 v55, v95, v95
	v_fmac_f32_e32 v55, v96, v96
	v_fmac_f32_e32 v55, v97, v97
	v_fmac_f32_e32 v55, v98, v98
	v_fmac_f32_e32 v55, v99, v99
	v_fmac_f32_e32 v55, v100, v100
	v_fmac_f32_e32 v55, v101, v101
	v_fmac_f32_e32 v55, v102, v102
	v_fmac_f32_e32 v55, v103, v103
	v_fmac_f32_e32 v55, v104, v104
	v_fmac_f32_e32 v55, v105, v105
	v_fmac_f32_e32 v55, v106, v106
	v_fmac_f32_e32 v55, v107, v107
	s_nop 1
	v_add_f32_dpp v55, v55, v55 row_shr:1 row_mask:0xf bank_mask:0xf bound_ctrl:0
	s_nop 1
	v_add_f32_dpp v55, v55, v55 row_shr:2 row_mask:0xf bank_mask:0xf bound_ctrl:0
	s_nop 1
	v_add_f32_dpp v55, v55, v55 row_shr:4 row_mask:0xf bank_mask:0xf bound_ctrl:0
	s_nop 1
	v_add_f32_dpp v55, v55, v55 row_shr:8 row_mask:0xf bank_mask:0xf bound_ctrl:0
	s_nop 1
	v_add_f32_dpp v55, v55, v55 row_bcast:15 row_mask:0xa bank_mask:0xf
	s_nop 1
	v_add_f32_dpp v55, v55, v55 row_bcast:31 row_mask:0xc bank_mask:0xf
	s_nop 1
	v_readlane_b32 vcc_lo, v55, 63
	s_nop 1
	v_mov_b32_e32 v55, vcc_lo
	v_fmamk_f32 v55, v55, 0x3a800000, v189
	v_rsq_f32_e32 v55, v55
	s_nop 0
	v_mul_f32_e32 v92, v92, v55
	v_mul_f32_e32 v93, v93, v55
	v_mul_f32_e32 v94, v94, v55
	v_mul_f32_e32 v95, v95, v55
	v_mul_f32_e32 v96, v96, v55
	v_mul_f32_e32 v97, v97, v55
	v_mul_f32_e32 v98, v98, v55
	v_mul_f32_e32 v99, v99, v55
	v_mul_f32_e32 v100, v100, v55
	v_mul_f32_e32 v101, v101, v55
	v_mul_f32_e32 v102, v102, v55
	v_mul_f32_e32 v103, v103, v55
	v_mul_f32_e32 v104, v104, v55
	v_mul_f32_e32 v105, v105, v55
	v_mul_f32_e32 v106, v106, v55
	v_mul_f32_e32 v107, v107, v55
	v_fma_f32 v92, v60, v92, v76
	v_fma_f32 v93, v61, v93, v77
	v_fma_f32 v94, v62, v94, v78
	v_fma_f32 v95, v63, v95, v79
	v_fma_f32 v96, v64, v96, v80
	v_fma_f32 v97, v65, v97, v81
	v_fma_f32 v98, v66, v98, v82
	v_fma_f32 v99, v67, v99, v83
	v_fma_f32 v100, v68, v100, v84
	v_fma_f32 v101, v69, v101, v85
	v_fma_f32 v102, v70, v102, v86
	v_fma_f32 v103, v71, v103, v87
	v_fma_f32 v104, v72, v104, v88
	v_fma_f32 v105, v73, v105, v89
	v_fma_f32 v106, v74, v106, v90
	v_fma_f32 v107, v75, v107, v91
	v_cvt_pk_bf16_f32 v16, v92, v93
	v_cvt_pk_bf16_f32 v17, v94, v95
	global_store_dwordx2 v[30:31], v[16:17], off
	v_cvt_pk_bf16_f32 v18, v96, v97
	v_cvt_pk_bf16_f32 v19, v98, v99
	global_store_dwordx2 v[30:31], v[18:19], off offset:512
	v_cvt_pk_bf16_f32 v20, v100, v101
	v_cvt_pk_bf16_f32 v21, v102, v103
	global_store_dwordx2 v[30:31], v[20:21], off offset:1024
	v_cvt_pk_bf16_f32 v22, v104, v105
	v_cvt_pk_bf16_f32 v23, v106, v107
	global_store_dwordx2 v[30:31], v[22:23], off offset:1536
	v_lshl_add_u64 v[30:31], v[30:31], 0, s[34:35]
	s_andn2_b64 exec, exec, s[12:13]
	s_cbranch_execz .LBB0_179
	v_lshl_add_u64 v[24:25], v[24:25], 0, s[88:89]
	v_cmp_lt_i32_e32 vcc, s81, v24
	s_or_b64 s[12:13], vcc, s[12:13]
	s_cbranch_vccnz .Lln0_nopf_b
	v_cmp_gt_i32_e32 vcc, s14, v24
	v_add_u32_e32 v0, 0xffffc000, v24
	v_mov_b32_e32 v4, s100
	v_mov_b32_e32 v5, s101
	v_mov_b32_e32 v6, s98
	v_mov_b32_e32 v7, s99
	v_cndmask_b32_e32 v2, v0, v24, vcc
	v_mov_b32_e32 v3, 0
	v_cndmask_b32_e32 v4, v4, v6, vcc
	v_cndmask_b32_e32 v5, v5, v7, vcc
	v_lshlrev_b64 v[2:3], 12, v[2:3]
	v_lshl_add_u64 v[2:3], v[4:5], 0, v[2:3]
	v_lshl_add_u64 v[2:3], v[2:3], 0, v[32:33]
	global_load_dwordx4 v[92:95], v[2:3], off
	global_load_dwordx4 v[96:99], v[2:3], off offset:1024
	global_load_dwordx4 v[100:103], v[2:3], off offset:2048
	global_load_dwordx4 v[104:107], v[2:3], off offset:3072
; DI unsigned pk2(float lo, float hi) { const hwf2_t v = {lo, hi}; const hwbf2_t b = __builtin_convertvector(v, hwbf2_t); return __builtin_bit_cast(unsigned, b); }
; DI float lo16(unsigned w) { return __uint_as_float(w << 16); }
; DI float hi16(unsigned w) { return __uint_as_float(w & 0xffff0000u); }
; DI float wave_sum(float v) { for (int o = 32; o >= 1; o >>= 1) v += __shfl_xor(v, o); return v; }
; DI void ln_pass(CP c, int mode, const float* gam, const float* bet, const float* modsc, const float* modsh, int bid, int nb, bool fin) {
;     ...
;     for (int r = bid * 8 + wave; r < MT; r += nb * 8) {
;         f32x4 v[4];
;         if (mode == 0) { const float* src = r < MP ? c->in[I_XP] + (size_t)r * DM : c->in[I_XS] + (size_t)(r - MP) * DM;
; #pragma unroll
;             for (int i = 0; i < 4; ++i) v[i] = *(const f32x4*)(src + lane * 4 + 256 * i); }
;         else {
; #pragma unroll
;             for (int i = 0; i < 4; ++i) { const u32x2 w = *(const u32x2*)(XB + (size_t)r * DM + lane * 4 + 256 * i); v[i] = (f32x4){lo16(w.x), hi16(w.x), lo16(w.y), hi16(w.y)}; } }
;         if (mode != 1) {
;             float s = 0.f;
; #pragma unroll
;             for (int i = 0; i < 4; ++i) s += v[i][0] + v[i][1] + v[i][2] + v[i][3];
;             const float mean = wave_sum(s) * (1.f / 1024.f); float q = 0.f;
; #pragma unroll
;             for (int i = 0; i < 4; ++i) { const f32x4 d = v[i] - mean; q += d[0] * d[0] + d[1] * d[1] + d[2] * d[2] + d[3] * d[3]; }
;             const float rstd = rsqrtf(wave_sum(q) * (1.f / 1024.f) + 1e-5f);
; #pragma unroll
;             for (int i = 0; i < 4; ++i) { const int col = lane * 4 + 256 * i; const f32x4 g = *(const f32x4*)(gam + col), b = *(const f32x4*)(bet + col);
;                 v[i] = (v[i] - mean) * rstd * g + b;
;                 if (fin) *(f32x4*)(c->out + (size_t)r * DM + col) = v[i];
;                 else { u32x2 w; w.x = pk2(v[i][0], v[i][1]); w.y = pk2(v[i][2], v[i][3]); *(u32x2*)(XB + (size_t)r * DM + col) = w; } }
.Lln0_nopf_b:
	s_waitcnt vmcnt(4)
	v_add_f32_e32 v0, v108, v109
	v_add_f32_e32 v0, v0, v110
	v_add_f32_e32 v0, v0, v111
	v_add_f32_e32 v0, v0, v112
	v_add_f32_e32 v0, v0, v113
	v_add_f32_e32 v0, v0, v114
	v_add_f32_e32 v0, v0, v115
	v_add_f32_e32 v0, v0, v116
	v_add_f32_e32 v0, v0, v117
	v_add_f32_e32 v0, v0, v118
	v_add_f32_e32 v0, v0, v119
	v_add_f32_e32 v0, v0, v120
	v_add_f32_e32 v0, v0, v121
	v_add_f32_e32 v0, v0, v122
	v_add_f32_e32 v0, v0, v123
	s_nop 1
	v_add_f32_dpp v0, v0, v0 row_shr:1 row_mask:0xf bank_mask:0xf bound_ctrl:0
	s_nop 1
	v_add_f32_dpp v0, v0, v0 row_shr:2 row_mask:0xf bank_mask:0xf bound_ctrl:0
	s_nop 1
	v_add_f32_dpp v0, v0, v0 row_shr:4 row_mask:0xf bank_mask:0xf bound_ctrl:0
	s_nop 1
	v_add_f32_dpp v0, v0, v0 row_shr:8 row_mask:0xf bank_mask:0xf bound_ctrl:0
	s_nop 1
	v_add_f32_dpp v0, v0, v0 row_bcast:15 row_mask:0xa bank_mask:0xf
	s_nop 1
	v_add_f32_dpp v0, v0, v0 row_bcast:31 row_mask:0xc bank_mask:0xf
	s_nop 1
	v_readlane_b32 vcc_lo, v0, 63
	s_nop 1
	v_mov_b32_e32 v0, vcc_lo
	v_fmac_f32_e32 v108, 0xba800000, v0
	v_fmac_f32_e32 v109, 0xba800000, v0
	v_fmac_f32_e32 v110, 0xba800000, v0
	v_fmac_f32_e32 v111, 0xba800000, v0
	v_fmac_f32_e32 v112, 0xba800000, v0
	v_fmac_f32_e32 v113, 0xba800000, v0
	v_fmac_f32_e32 v114, 0xba800000, v0
	v_fmac_f32_e32 v115, 0xba800000, v0
	v_fmac_f32_e32 v116, 0xba800000, v0
	v_fmac_f32_e32 v117, 0xba800000, v0
	v_fmac_f32_e32 v118, 0xba800000, v0
	v_fmac_f32_e32 v119, 0xba800000, v0
	v_fmac_f32_e32 v120, 0xba800000, v0
	v_fmac_f32_e32 v121, 0xba800000, v0
	v_fmac_f32_e32 v122, 0xba800000, v0
	v_fmac_f32_e32 v123, 0xba800000, v0
	v_mul_f32_e32 v55, v108, v108
	v_fmac_f32_e32 v55, v109, v109
	v_fmac_f32_e32 v55, v110, v110
	v_fmac_f32_e32 v55, v111, v111
	v_fmac_f32_e32 v55, v112, v112
	v_fmac_f32_e32 v55, v113, v113
	v_fmac_f32_e32 v55, v114, v114
	v_fmac_f32_e32 v55, v115, v115
	v_fmac_f32_e32 v55, v116, v116
	v_fmac_f32_e32 v55, v117, v117
	v_fmac_f32_e32 v55, v118, v118
	v_fmac_f32_e32 v55, v119, v119
	v_fmac_f32_e32 v55, v120, v120
	v_fmac_f32_e32 v55, v121, v121
	v_fmac_f32_e32 v55, v122, v122
	v_fmac_f32_e32 v55, v123, v123
	s_nop 1
	v_add_f32_dpp v55, v55, v55 row_shr:1 row_mask:0xf bank_mask:0xf bound_ctrl:0
	s_nop 1
	v_add_f32_dpp v55, v55, v55 row_shr:2 row_mask:0xf bank_mask:0xf bound_ctrl:0
	s_nop 1
	v_add_f32_dpp v55, v55, v55 row_shr:4 row_mask:0xf bank_mask:0xf bound_ctrl:0
	s_nop 1
	v_add_f32_dpp v55, v55, v55 row_shr:8 row_mask:0xf bank_mask:0xf bound_ctrl:0
	s_nop 1
	v_add_f32_dpp v55, v55, v55 row_bcast:15 row_mask:0xa bank_mask:0xf
	s_nop 1
	v_add_f32_dpp v55, v55, v55 row_bcast:31 row_mask:0xc bank_mask:0xf
	s_nop 1
	v_readlane_b32 vcc_lo, v55, 63
	s_nop 1
	v_mov_b32_e32 v55, vcc_lo
	v_fmamk_f32 v55, v55, 0x3a800000, v189
	v_rsq_f32_e32 v55, v55
	s_nop 0
	v_mul_f32_e32 v108, v108, v55
	v_mul_f32_e32 v109, v109, v55
	v_mul_f32_e32 v110, v110, v55
	v_mul_f32_e32 v111, v111, v55
	v_mul_f32_e32 v112, v112, v55
	v_mul_f32_e32 v113, v113, v55
	v_mul_f32_e32 v114, v114, v55
	v_mul_f32_e32 v115, v115, v55
	v_mul_f32_e32 v116, v116, v55
	v_mul_f32_e32 v117, v117, v55
	v_mul_f32_e32 v118, v118, v55
	v_mul_f32_e32 v119, v119, v55
	v_mul_f32_e32 v120, v120, v55
	v_mul_f32_e32 v121, v121, v55
	v_mul_f32_e32 v122, v122, v55
	v_mul_f32_e32 v123, v123, v55
	v_fma_f32 v108, v60, v108, v76
	v_fma_f32 v109, v61, v109, v77
	v_fma_f32 v110, v62, v110, v78
	v_fma_f32 v111, v63, v111, v79
	v_fma_f32 v112, v64, v112, v80
	v_fma_f32 v113, v65, v113, v81
	v_fma_f32 v114, v66, v114, v82
	v_fma_f32 v115, v67, v115, v83
	v_fma_f32 v116, v68, v116, v84
	v_fma_f32 v117, v69, v117, v85
	v_fma_f32 v118, v70, v118, v86
	v_fma_f32 v119, v71, v119, v87
	v_fma_f32 v120, v72, v120, v88
	v_fma_f32 v121, v73, v121, v89
	v_fma_f32 v122, v74, v122, v90
	v_fma_f32 v123, v75, v123, v91
	v_cvt_pk_bf16_f32 v16, v108, v109
	v_cvt_pk_bf16_f32 v17, v110, v111
	global_store_dwordx2 v[30:31], v[16:17], off
	v_cvt_pk_bf16_f32 v18, v112, v113
	v_cvt_pk_bf16_f32 v19, v114, v115
	global_store_dwordx2 v[30:31], v[18:19], off offset:512
	v_cvt_pk_bf16_f32 v20, v116, v117
	v_cvt_pk_bf16_f32 v21, v118, v119
	global_store_dwordx2 v[30:31], v[20:21], off offset:1024
	v_cvt_pk_bf16_f32 v22, v120, v121
	v_cvt_pk_bf16_f32 v23, v122, v123
	global_store_dwordx2 v[30:31], v[22:23], off offset:1536
	v_lshl_add_u64 v[30:31], v[30:31], 0, s[34:35]
	s_andn2_b64 exec, exec, s[12:13]
	s_cbranch_execnz .LBB0_178

; DI unsigned pk2(float lo, float hi) { const hwf2_t v = {lo, hi}; const hwbf2_t b = __builtin_convertvector(v, hwbf2_t); return __builtin_bit_cast(unsigned, b); }
; DI float lo16(unsigned w) { return __uint_as_float(w << 16); }
; DI float hi16(unsigned w) { return __uint_as_float(w & 0xffff0000u); }
; DI float wave_sum(float v) { for (int o = 32; o >= 1; o >>= 1) v += __shfl_xor(v, o); return v; }
; DI void ln_pass(CP c, int mode, const float* gam, const float* bet, const float* modsc, const float* modsh, int bid, int nb, bool fin) {
;     ...
;         else {
; #pragma unroll
;             for (int i = 0; i < 4; ++i) { const u32x2 w = *(const u32x2*)(XB + (size_t)r * DM + lane * 4 + 256 * i); v[i] = (f32x4){lo16(w.x), hi16(w.x), lo16(w.y), hi16(w.y)}; } }
;         if (mode != 1) {
;             float s = 0.f;
; #pragma unroll
;             for (int i = 0; i < 4; ++i) s += v[i][0] + v[i][1] + v[i][2] + v[i][3];
;             const float mean = wave_sum(s) * (1.f / 1024.f); float q = 0.f;
; #pragma unroll
;             for (int i = 0; i < 4; ++i) { const f32x4 d = v[i] - mean; q += d[0] * d[0] + d[1] * d[1] + d[2] * d[2] + d[3] * d[3]; }
;             const float rstd = rsqrtf(wave_sum(q) * (1.f / 1024.f) + 1e-5f);
; #pragma unroll
;             for (int i = 0; i < 4; ++i) { const int col = lane * 4 + 256 * i; const f32x4 g = *(const f32x4*)(gam + col), b = *(const f32x4*)(bet + col);
;                 v[i] = (v[i] - mean) * rstd * g + b;
;                 if (fin) *(f32x4*)(c->out + (size_t)r * DM + col) = v[i];
;                 else { u32x2 w; w.x = pk2(v[i][0], v[i][1]); w.y = pk2(v[i][2], v[i][3]); *(u32x2*)(XB + (size_t)r * DM + col) = w; } }
.LBB0_410:
	v_lshl_add_u64 v[56:57], v[26:27], 0, s[44:45]
	global_load_dwordx2 v[100:101], v[56:57], off offset:-1024
	global_load_dwordx2 v[102:103], v[56:57], off offset:-512
	global_load_dwordx2 v[104:105], v[56:57], off
	global_load_dwordx2 v[106:107], v[56:57], off offset:512
	s_waitcnt vmcnt(4)
	v_lshlrev_b32_e32 v140, 16, v92
	v_and_b32_e32 v141, 0xffff0000, v92
	v_lshlrev_b32_e32 v142, 16, v93
	v_and_b32_e32 v143, 0xffff0000, v93
	v_lshlrev_b32_e32 v144, 16, v94
	v_and_b32_e32 v145, 0xffff0000, v94
	v_lshlrev_b32_e32 v146, 16, v95
	v_and_b32_e32 v147, 0xffff0000, v95
	v_lshlrev_b32_e32 v148, 16, v96
	v_and_b32_e32 v149, 0xffff0000, v96
	v_lshlrev_b32_e32 v150, 16, v97
	v_and_b32_e32 v151, 0xffff0000, v97
	v_lshlrev_b32_e32 v152, 16, v98
	v_and_b32_e32 v153, 0xffff0000, v98
	v_lshlrev_b32_e32 v154, 16, v99
	v_and_b32_e32 v155, 0xffff0000, v99
	v_add_f32_e32 v0, v140, v141
	v_add_f32_e32 v0, v0, v142
	v_add_f32_e32 v0, v0, v143
	v_add_f32_e32 v0, v0, v144
	v_add_f32_e32 v0, v0, v145
	v_add_f32_e32 v0, v0, v146
	v_add_f32_e32 v0, v0, v147
	v_add_f32_e32 v0, v0, v148
	v_add_f32_e32 v0, v0, v149
	v_add_f32_e32 v0, v0, v150
	v_add_f32_e32 v0, v0, v151
	v_add_f32_e32 v0, v0, v152
	v_add_f32_e32 v0, v0, v153
	v_add_f32_e32 v0, v0, v154
	v_add_f32_e32 v0, v0, v155
	s_nop 1
	v_add_f32_dpp v0, v0, v0 row_shr:1 row_mask:0xf bank_mask:0xf bound_ctrl:0
	s_nop 1
	v_add_f32_dpp v0, v0, v0 row_shr:2 row_mask:0xf bank_mask:0xf bound_ctrl:0
	s_nop 1
	v_add_f32_dpp v0, v0, v0 row_shr:4 row_mask:0xf bank_mask:0xf bound_ctrl:0
	s_nop 1
	v_add_f32_dpp v0, v0, v0 row_shr:8 row_mask:0xf bank_mask:0xf bound_ctrl:0
	s_nop 1
	v_add_f32_dpp v0, v0, v0 row_bcast:15 row_mask:0xa bank_mask:0xf
	s_nop 1
	v_add_f32_dpp v0, v0, v0 row_bcast:31 row_mask:0xc bank_mask:0xf
	s_nop 1
	v_readlane_b32 vcc_lo, v0, 63
	s_nop 1
	v_mov_b32_e32 v0, vcc_lo
	v_fmac_f32_e32 v140, 0xba800000, v0
	v_fmac_f32_e32 v141, 0xba800000, v0
	v_fmac_f32_e32 v142, 0xba800000, v0
	v_fmac_f32_e32 v143, 0xba800000, v0
	v_fmac_f32_e32 v144, 0xba800000, v0
	v_fmac_f32_e32 v145, 0xba800000, v0
	v_fmac_f32_e32 v146, 0xba800000, v0
	v_fmac_f32_e32 v147, 0xba800000, v0
	v_fmac_f32_e32 v148, 0xba800000, v0
	v_fmac_f32_e32 v149, 0xba800000, v0
	v_fmac_f32_e32 v150, 0xba800000, v0
	v_fmac_f32_e32 v151, 0xba800000, v0
	v_fmac_f32_e32 v152, 0xba800000, v0
	v_fmac_f32_e32 v153, 0xba800000, v0
	v_fmac_f32_e32 v154, 0xba800000, v0
	v_fmac_f32_e32 v155, 0xba800000, v0
	v_mul_f32_e32 v55, v140, v140
	v_fmac_f32_e32 v55, v141, v141
	v_fmac_f32_e32 v55, v142, v142
	v_fmac_f32_e32 v55, v143, v143
	v_fmac_f32_e32 v55, v144, v144
	v_fmac_f32_e32 v55, v145, v145
	v_fmac_f32_e32 v55, v146, v146
	v_fmac_f32_e32 v55, v147, v147
	v_fmac_f32_e32 v55, v148, v148
	v_fmac_f32_e32 v55, v149, v149
	v_fmac_f32_e32 v55, v150, v150
	v_fmac_f32_e32 v55, v151, v151
	v_fmac_f32_e32 v55, v152, v152
	v_fmac_f32_e32 v55, v153, v153
	v_fmac_f32_e32 v55, v154, v154
	v_fmac_f32_e32 v55, v155, v155
	s_nop 1
	v_add_f32_dpp v55, v55, v55 row_shr:1 row_mask:0xf bank_mask:0xf bound_ctrl:0
	s_nop 1
	v_add_f32_dpp v55, v55, v55 row_shr:2 row_mask:0xf bank_mask:0xf bound_ctrl:0
	s_nop 1
	v_add_f32_dpp v55, v55, v55 row_shr:4 row_mask:0xf bank_mask:0xf bound_ctrl:0
	s_nop 1
	v_add_f32_dpp v55, v55, v55 row_shr:8 row_mask:0xf bank_mask:0xf bound_ctrl:0
	s_nop 1
	v_add_f32_dpp v55, v55, v55 row_bcast:15 row_mask:0xa bank_mask:0xf
	s_nop 1
	v_add_f32_dpp v55, v55, v55 row_bcast:31 row_mask:0xc bank_mask:0xf
	s_nop 1
	v_readlane_b32 vcc_lo, v55, 63
	s_nop 1
	v_mov_b32_e32 v55, vcc_lo
	v_fmamk_f32 v55, v55, 0x3a800000, v189
	v_rsq_f32_e32 v55, v55
	s_nop 0
	v_mul_f32_e32 v140, v140, v55
	v_mul_f32_e32 v141, v141, v55
	v_mul_f32_e32 v142, v142, v55
	v_mul_f32_e32 v143, v143, v55
	v_mul_f32_e32 v144, v144, v55
	v_mul_f32_e32 v145, v145, v55
	v_mul_f32_e32 v146, v146, v55
	v_mul_f32_e32 v147, v147, v55
	v_mul_f32_e32 v148, v148, v55
	v_mul_f32_e32 v149, v149, v55
	v_mul_f32_e32 v150, v150, v55
	v_mul_f32_e32 v151, v151, v55
	v_mul_f32_e32 v152, v152, v55
	v_mul_f32_e32 v153, v153, v55
	v_mul_f32_e32 v154, v154, v55
	v_mul_f32_e32 v155, v155, v55
	v_fma_f32 v140, v60, v140, v76
	v_fma_f32 v141, v61, v141, v77
	v_fma_f32 v142, v62, v142, v78
	v_fma_f32 v143, v63, v143, v79
	v_fma_f32 v144, v64, v144, v80
	v_fma_f32 v145, v65, v145, v81
	v_fma_f32 v146, v66, v146, v82
	v_fma_f32 v147, v67, v147, v83
	v_fma_f32 v148, v68, v148, v84
	v_fma_f32 v149, v69, v149, v85
	v_fma_f32 v150, v70, v150, v86
	v_fma_f32 v151, v71, v151, v87
	v_fma_f32 v152, v72, v152, v88
	v_fma_f32 v153, v73, v153, v89
	v_fma_f32 v154, v74, v154, v90
	v_fma_f32 v155, v75, v155, v91
	global_store_dwordx4 v[28:29], v[140:143], off offset:-3072
	global_store_dwordx4 v[28:29], v[144:147], off offset:-2048
	global_store_dwordx4 v[28:29], v[148:151], off offset:-1024
	global_store_dwordx4 v[28:29], v[152:155], off
	v_add_u32_e32 v46, s76, v46
	v_mov_b32_e32 v26, v56
	v_mov_b32_e32 v27, v57
	v_lshl_add_u64 v[28:29], v[28:29], 0, s[30:31]
	v_cmp_lt_i32_e32 vcc, s81, v46
	s_or_b64 s[6:7], vcc, s[6:7]
	s_andn2_b64 exec, exec, s[6:7]
	s_cbranch_execz .LBB0_411
; DI unsigned pk2(float lo, float hi) { const hwf2_t v = {lo, hi}; const hwbf2_t b = __builtin_convertvector(v, hwbf2_t); return __builtin_bit_cast(unsigned, b); }
; DI float lo16(unsigned w) { return __uint_as_float(w << 16); }
; DI float hi16(unsigned w) { return __uint_as_float(w & 0xffff0000u); }
; DI float wave_sum(float v) { for (int o = 32; o >= 1; o >>= 1) v += __shfl_xor(v, o); return v; }
; DI void ln_pass(CP c, int mode, const float* gam, const float* bet, const float* modsc, const float* modsh, int bid, int nb, bool fin) {
;     ...
;         else {
; #pragma unroll
;             for (int i = 0; i < 4; ++i) { const u32x2 w = *(const u32x2*)(XB + (size_t)r * DM + lane * 4 + 256 * i); v[i] = (f32x4){lo16(w.x), hi16(w.x), lo16(w.y), hi16(w.y)}; } }
;         if (mode != 1) {
;             float s = 0.f;
; #pragma unroll
;             for (int i = 0; i < 4; ++i) s += v[i][0] + v[i][1] + v[i][2] + v[i][3];
;             const float mean = wave_sum(s) * (1.f / 1024.f); float q = 0.f;
; #pragma unroll
;             for (int i = 0; i < 4; ++i) { const f32x4 d = v[i] - mean; q += d[0] * d[0] + d[1] * d[1] + d[2] * d[2] + d[3] * d[3]; }
;             const float rstd = rsqrtf(wave_sum(q) * (1.f / 1024.f) + 1e-5f);
; #pragma unroll
;             for (int i = 0; i < 4; ++i) { const int col = lane * 4 + 256 * i; const f32x4 g = *(const f32x4*)(gam + col), b = *(const f32x4*)(bet + col);
;                 v[i] = (v[i] - mean) * rstd * g + b;
;                 if (fin) *(f32x4*)(c->out + (size_t)r * DM + col) = v[i];
;                 else { u32x2 w; w.x = pk2(v[i][0], v[i][1]); w.y = pk2(v[i][2], v[i][3]); *(u32x2*)(XB + (size_t)r * DM + col) = w; } }
	v_lshl_add_u64 v[56:57], v[26:27], 0, s[44:45]
	global_load_dwordx2 v[92:93], v[56:57], off offset:-1024
	global_load_dwordx2 v[94:95], v[56:57], off offset:-512
	global_load_dwordx2 v[96:97], v[56:57], off
	global_load_dwordx2 v[98:99], v[56:57], off offset:512
	s_waitcnt vmcnt(4)
	v_lshlrev_b32_e32 v140, 16, v100
	v_and_b32_e32 v141, 0xffff0000, v100
	v_lshlrev_b32_e32 v142, 16, v101
	v_and_b32_e32 v143, 0xffff0000, v101
	v_lshlrev_b32_e32 v144, 16, v102
	v_and_b32_e32 v145, 0xffff0000, v102
	v_lshlrev_b32_e32 v146, 16, v103
	v_and_b32_e32 v147, 0xffff0000, v103
	v_lshlrev_b32_e32 v148, 16, v104
	v_and_b32_e32 v149, 0xffff0000, v104
	v_lshlrev_b32_e32 v150, 16, v105
	v_and_b32_e32 v151, 0xffff0000, v105
	v_lshlrev_b32_e32 v152, 16, v106
	v_and_b32_e32 v153, 0xffff0000, v106
	v_lshlrev_b32_e32 v154, 16, v107
	v_and_b32_e32 v155, 0xffff0000, v107
	v_add_f32_e32 v0, v140, v141
	v_add_f32_e32 v0, v0, v142
	v_add_f32_e32 v0, v0, v143
	v_add_f32_e32 v0, v0, v144
	v_add_f32_e32 v0, v0, v145
	v_add_f32_e32 v0, v0, v146
	v_add_f32_e32 v0, v0, v147
	v_add_f32_e32 v0, v0, v148
	v_add_f32_e32 v0, v0, v149
	v_add_f32_e32 v0, v0, v150
	v_add_f32_e32 v0, v0, v151
	v_add_f32_e32 v0, v0, v152
	v_add_f32_e32 v0, v0, v153
	v_add_f32_e32 v0, v0, v154
	v_add_f32_e32 v0, v0, v155
	s_nop 1
	v_add_f32_dpp v0, v0, v0 row_shr:1 row_mask:0xf bank_mask:0xf bound_ctrl:0
	s_nop 1
	v_add_f32_dpp v0, v0, v0 row_shr:2 row_mask:0xf bank_mask:0xf bound_ctrl:0
	s_nop 1
	v_add_f32_dpp v0, v0, v0 row_shr:4 row_mask:0xf bank_mask:0xf bound_ctrl:0
	s_nop 1
	v_add_f32_dpp v0, v0, v0 row_shr:8 row_mask:0xf bank_mask:0xf bound_ctrl:0
	s_nop 1
	v_add_f32_dpp v0, v0, v0 row_bcast:15 row_mask:0xa bank_mask:0xf
	s_nop 1
	v_add_f32_dpp v0, v0, v0 row_bcast:31 row_mask:0xc bank_mask:0xf
	s_nop 1
	v_readlane_b32 vcc_lo, v0, 63
	s_nop 1
	v_mov_b32_e32 v0, vcc_lo
	v_fmac_f32_e32 v140, 0xba800000, v0
	v_fmac_f32_e32 v141, 0xba800000, v0
	v_fmac_f32_e32 v142, 0xba800000, v0
	v_fmac_f32_e32 v143, 0xba800000, v0
	v_fmac_f32_e32 v144, 0xba800000, v0
	v_fmac_f32_e32 v145, 0xba800000, v0
	v_fmac_f32_e32 v146, 0xba800000, v0
	v_fmac_f32_e32 v147, 0xba800000, v0
	v_fmac_f32_e32 v148, 0xba800000, v0
	v_fmac_f32_e32 v149, 0xba800000, v0
	v_fmac_f32_e32 v150, 0xba800000, v0
	v_fmac_f32_e32 v151, 0xba800000, v0
	v_fmac_f32_e32 v152, 0xba800000, v0
	v_fmac_f32_e32 v153, 0xba800000, v0
	v_fmac_f32_e32 v154, 0xba800000, v0
	v_fmac_f32_e32 v155, 0xba800000, v0
	v_mul_f32_e32 v55, v140, v140
	v_fmac_f32_e32 v55, v141, v141
	v_fmac_f32_e32 v55, v142, v142
	v_fmac_f32_e32 v55, v143, v143
	v_fmac_f32_e32 v55, v144, v144
	v_fmac_f32_e32 v55, v145, v145
	v_fmac_f32_e32 v55, v146, v146
	v_fmac_f32_e32 v55, v147, v147
	v_fmac_f32_e32 v55, v148, v148
	v_fmac_f32_e32 v55, v149, v149
	v_fmac_f32_e32 v55, v150, v150
	v_fmac_f32_e32 v55, v151, v151
	v_fmac_f32_e32 v55, v152, v152
	v_fmac_f32_e32 v55, v153, v153
	v_fmac_f32_e32 v55, v154, v154
	v_fmac_f32_e32 v55, v155, v155
	s_nop 1
	v_add_f32_dpp v55, v55, v55 row_shr:1 row_mask:0xf bank_mask:0xf bound_ctrl:0
	s_nop 1
	v_add_f32_dpp v55, v55, v55 row_shr:2 row_mask:0xf bank_mask:0xf bound_ctrl:0
	s_nop 1
	v_add_f32_dpp v55, v55, v55 row_shr:4 row_mask:0xf bank_mask:0xf bound_ctrl:0
	s_nop 1
	v_add_f32_dpp v55, v55, v55 row_shr:8 row_mask:0xf bank_mask:0xf bound_ctrl:0
	s_nop 1
	v_add_f32_dpp v55, v55, v55 row_bcast:15 row_mask:0xa bank_mask:0xf
	s_nop 1
	v_add_f32_dpp v55, v55, v55 row_bcast:31 row_mask:0xc bank_mask:0xf
	s_nop 1
	v_readlane_b32 vcc_lo, v55, 63
	s_nop 1
	v_mov_b32_e32 v55, vcc_lo
	v_fmamk_f32 v55, v55, 0x3a800000, v189
	v_rsq_f32_e32 v55, v55
	s_nop 0
	v_mul_f32_e32 v140, v140, v55
	v_mul_f32_e32 v141, v141, v55
	v_mul_f32_e32 v142, v142, v55
	v_mul_f32_e32 v143, v143, v55
	v_mul_f32_e32 v144, v144, v55
	v_mul_f32_e32 v145, v145, v55
	v_mul_f32_e32 v146, v146, v55
	v_mul_f32_e32 v147, v147, v55
	v_mul_f32_e32 v148, v148, v55
	v_mul_f32_e32 v149, v149, v55
	v_mul_f32_e32 v150, v150, v55
	v_mul_f32_e32 v151, v151, v55
	v_mul_f32_e32 v152, v152, v55
	v_mul_f32_e32 v153, v153, v55
	v_mul_f32_e32 v154, v154, v55
	v_mul_f32_e32 v155, v155, v55
	v_fma_f32 v140, v60, v140, v76
	v_fma_f32 v141, v61, v141, v77
	v_fma_f32 v142, v62, v142, v78
	v_fma_f32 v143, v63, v143, v79
	v_fma_f32 v144, v64, v144, v80
	v_fma_f32 v145, v65, v145, v81
	v_fma_f32 v146, v66, v146, v82
	v_fma_f32 v147, v67, v147, v83
	v_fma_f32 v148, v68, v148, v84
	v_fma_f32 v149, v69, v149, v85
	v_fma_f32 v150, v70, v150, v86
	v_fma_f32 v151, v71, v151, v87
	v_fma_f32 v152, v72, v152, v88
	v_fma_f32 v153, v73, v153, v89
	v_fma_f32 v154, v74, v154, v90
	v_fma_f32 v155, v75, v155, v91
	global_store_dwordx4 v[28:29], v[140:143], off offset:-3072
	global_store_dwordx4 v[28:29], v[144:147], off offset:-2048
	global_store_dwordx4 v[28:29], v[148:151], off offset:-1024
	global_store_dwordx4 v[28:29], v[152:155], off
	v_add_u32_e32 v46, s76, v46
	v_mov_b32_e32 v26, v56
	v_mov_b32_e32 v27, v57
	v_lshl_add_u64 v[28:29], v[28:29], 0, s[30:31]
	v_cmp_lt_i32_e32 vcc, s81, v46
	s_or_b64 s[6:7], vcc, s[6:7]
	s_andn2_b64 exec, exec, s[6:7]
	s_cbranch_execnz .LBB0_410

; DI unsigned pk2(float lo, float hi) { const hwf2_t v = {lo, hi}; const hwbf2_t b = __builtin_convertvector(v, hwbf2_t); return __builtin_bit_cast(unsigned, b); }
; DI float lo16(unsigned w) { return __uint_as_float(w << 16); }
; DI float hi16(unsigned w) { return __uint_as_float(w & 0xffff0000u); }
; DI float wave_sum(float v) { for (int o = 32; o >= 1; o >>= 1) v += __shfl_xor(v, o); return v; }
; DI void ln_pass(CP c, int mode, const float* gam, const float* bet, const float* modsc, const float* modsh, int bid, int nb, bool fin) {
;     ...
;         else {
; #pragma unroll
;             for (int i = 0; i < 4; ++i) { const u32x2 w = *(const u32x2*)(XB + (size_t)r * DM + lane * 4 + 256 * i); v[i] = (f32x4){lo16(w.x), hi16(w.x), lo16(w.y), hi16(w.y)}; } }
;         if (mode != 1) {
;             float s = 0.f;
; #pragma unroll
;             for (int i = 0; i < 4; ++i) s += v[i][0] + v[i][1] + v[i][2] + v[i][3];
;             const float mean = wave_sum(s) * (1.f / 1024.f); float q = 0.f;
; #pragma unroll
;             for (int i = 0; i < 4; ++i) { const f32x4 d = v[i] - mean; q += d[0] * d[0] + d[1] * d[1] + d[2] * d[2] + d[3] * d[3]; }
;             const float rstd = rsqrtf(wave_sum(q) * (1.f / 1024.f) + 1e-5f);
; #pragma unroll
;             for (int i = 0; i < 4; ++i) { const int col = lane * 4 + 256 * i; const f32x4 g = *(const f32x4*)(gam + col), b = *(const f32x4*)(bet + col);
;                 v[i] = (v[i] - mean) * rstd * g + b;
;                 if (fin) *(f32x4*)(c->out + (size_t)r * DM + col) = v[i];
;                 else { u32x2 w; w.x = pk2(v[i][0], v[i][1]); w.y = pk2(v[i][2], v[i][3]); *(u32x2*)(XB + (size_t)r * DM + col) = w; } }
;         }
;         if (modsc) { const int mr = modrow_of(r);
; #pragma unroll
;             for (int i = 0; i < 4; ++i) { const int col = lane * 4 + 256 * i; const f32x4 sc = *(const f32x4*)(modsc + (size_t)mr * 12288 + col), sh = *(const f32x4*)(modsh + (size_t)mr * 12288 + col);
;                 const f32x4 h = v[i] * (sc + 1.0f) + sh; u32x2 w; w.x = pk2(h[0], h[1]); w.y = pk2(h[2], h[3]);
;                 *(u32x2*)(H + (size_t)r * DM + col) = w; } }
.LBB0_415:
	v_add_u32_e32 v0, 0xffffc000, v30
	v_lshrrev_b32_e32 v0, 4, v0
	v_add_u32_e32 v0, 1, v0
	v_cmp_lt_i32_e32 vcc, s3, v30
	s_nop 1
	v_cndmask_b32_e32 v0, 0, v0, vcc
	v_mad_u64_u32 v[24:25], s[8:9], v0, s86, v[6:7]
	v_mad_u64_u32 v[46:47], s[8:9], v0, s86, v[8:9]
	global_load_dwordx4 v[108:111], v[24:25], off
	global_load_dwordx4 v[112:115], v[24:25], off offset:1024
	global_load_dwordx4 v[116:119], v[24:25], off offset:2048
	global_load_dwordx4 v[120:123], v[24:25], off offset:3072
	global_load_dwordx4 v[124:127], v[46:47], off
	global_load_dwordx4 v[128:131], v[46:47], off offset:1024
	global_load_dwordx4 v[132:135], v[46:47], off offset:2048
	global_load_dwordx4 v[136:139], v[46:47], off offset:3072
	s_waitcnt vmcnt(8)
	v_lshl_add_u64 v[48:49], v[12:13], 0, s[44:45]
	global_load_dwordx2 v[100:101], v[48:49], off
	global_load_dwordx2 v[102:103], v[48:49], off offset:512
	global_load_dwordx2 v[104:105], v[48:49], off offset:1024
	global_load_dwordx2 v[106:107], v[48:49], off offset:1536
	v_lshlrev_b32_e32 v140, 16, v92
	v_and_b32_e32 v141, 0xffff0000, v92
	v_lshlrev_b32_e32 v142, 16, v93
	v_and_b32_e32 v143, 0xffff0000, v93
	v_lshlrev_b32_e32 v144, 16, v94
	v_and_b32_e32 v145, 0xffff0000, v94
	v_lshlrev_b32_e32 v146, 16, v95
	v_and_b32_e32 v147, 0xffff0000, v95
	v_lshlrev_b32_e32 v148, 16, v96
	v_and_b32_e32 v149, 0xffff0000, v96
	v_lshlrev_b32_e32 v150, 16, v97
	v_and_b32_e32 v151, 0xffff0000, v97
	v_lshlrev_b32_e32 v152, 16, v98
	v_and_b32_e32 v153, 0xffff0000, v98
	v_lshlrev_b32_e32 v154, 16, v99
	v_and_b32_e32 v155, 0xffff0000, v99
	v_add_f32_e32 v0, v140, v141
	v_add_f32_e32 v0, v0, v142
	v_add_f32_e32 v0, v0, v143
	v_add_f32_e32 v0, v0, v144
	v_add_f32_e32 v0, v0, v145
	v_add_f32_e32 v0, v0, v146
	v_add_f32_e32 v0, v0, v147
	v_add_f32_e32 v0, v0, v148
	v_add_f32_e32 v0, v0, v149
	v_add_f32_e32 v0, v0, v150
	v_add_f32_e32 v0, v0, v151
	v_add_f32_e32 v0, v0, v152
	v_add_f32_e32 v0, v0, v153
	v_add_f32_e32 v0, v0, v154
	v_add_f32_e32 v0, v0, v155
	s_nop 1
	v_add_f32_dpp v0, v0, v0 row_shr:1 row_mask:0xf bank_mask:0xf bound_ctrl:0
	s_nop 1
	v_add_f32_dpp v0, v0, v0 row_shr:2 row_mask:0xf bank_mask:0xf bound_ctrl:0
	s_nop 1
	v_add_f32_dpp v0, v0, v0 row_shr:4 row_mask:0xf bank_mask:0xf bound_ctrl:0
	s_nop 1
	v_add_f32_dpp v0, v0, v0 row_shr:8 row_mask:0xf bank_mask:0xf bound_ctrl:0
	s_nop 1
	v_add_f32_dpp v0, v0, v0 row_bcast:15 row_mask:0xa bank_mask:0xf
	s_nop 1
	v_add_f32_dpp v0, v0, v0 row_bcast:31 row_mask:0xc bank_mask:0xf
	s_nop 1
	v_readlane_b32 vcc_lo, v0, 63
	s_nop 1
	v_mov_b32_e32 v0, vcc_lo
	v_fmac_f32_e32 v140, 0xba800000, v0
	v_fmac_f32_e32 v141, 0xba800000, v0
	v_fmac_f32_e32 v142, 0xba800000, v0
	v_fmac_f32_e32 v143, 0xba800000, v0
	v_fmac_f32_e32 v144, 0xba800000, v0
	v_fmac_f32_e32 v145, 0xba800000, v0
	v_fmac_f32_e32 v146, 0xba800000, v0
	v_fmac_f32_e32 v147, 0xba800000, v0
	v_fmac_f32_e32 v148, 0xba800000, v0
	v_fmac_f32_e32 v149, 0xba800000, v0
	v_fmac_f32_e32 v150, 0xba800000, v0
	v_fmac_f32_e32 v151, 0xba800000, v0
	v_fmac_f32_e32 v152, 0xba800000, v0
	v_fmac_f32_e32 v153, 0xba800000, v0
	v_fmac_f32_e32 v154, 0xba800000, v0
	v_fmac_f32_e32 v155, 0xba800000, v0
	v_mul_f32_e32 v15, v140, v140
	v_fmac_f32_e32 v15, v141, v141
	v_fmac_f32_e32 v15, v142, v142
	v_fmac_f32_e32 v15, v143, v143
	v_fmac_f32_e32 v15, v144, v144
	v_fmac_f32_e32 v15, v145, v145
	v_fmac_f32_e32 v15, v146, v146
	v_fmac_f32_e32 v15, v147, v147
	v_fmac_f32_e32 v15, v148, v148
	v_fmac_f32_e32 v15, v149, v149
	v_fmac_f32_e32 v15, v150, v150
	v_fmac_f32_e32 v15, v151, v151
	v_fmac_f32_e32 v15, v152, v152
	v_fmac_f32_e32 v15, v153, v153
	v_fmac_f32_e32 v15, v154, v154
	v_fmac_f32_e32 v15, v155, v155
	s_nop 1
	v_add_f32_dpp v15, v15, v15 row_shr:1 row_mask:0xf bank_mask:0xf bound_ctrl:0
	s_nop 1
	v_add_f32_dpp v15, v15, v15 row_shr:2 row_mask:0xf bank_mask:0xf bound_ctrl:0
	s_nop 1
	v_add_f32_dpp v15, v15, v15 row_shr:4 row_mask:0xf bank_mask:0xf bound_ctrl:0
	s_nop 1
	v_add_f32_dpp v15, v15, v15 row_shr:8 row_mask:0xf bank_mask:0xf bound_ctrl:0
	s_nop 1
	v_add_f32_dpp v15, v15, v15 row_bcast:15 row_mask:0xa bank_mask:0xf
	s_nop 1
	v_add_f32_dpp v15, v15, v15 row_bcast:31 row_mask:0xc bank_mask:0xf
	s_nop 1
	v_readlane_b32 vcc_lo, v15, 63
	s_nop 1
	v_mov_b32_e32 v15, vcc_lo
	v_fmamk_f32 v15, v15, 0x3a800000, v189
	v_rsq_f32_e32 v15, v15
	s_nop 0
	v_mul_f32_e32 v140, v140, v15
	v_mul_f32_e32 v141, v141, v15
	v_mul_f32_e32 v142, v142, v15
	v_mul_f32_e32 v143, v143, v15
	v_mul_f32_e32 v144, v144, v15
	v_mul_f32_e32 v145, v145, v15
	v_mul_f32_e32 v146, v146, v15
	v_mul_f32_e32 v147, v147, v15
	v_mul_f32_e32 v148, v148, v15
	v_mul_f32_e32 v149, v149, v15
	v_mul_f32_e32 v150, v150, v15
	v_mul_f32_e32 v151, v151, v15
	v_mul_f32_e32 v152, v152, v15
	v_mul_f32_e32 v153, v153, v15
	v_mul_f32_e32 v154, v154, v15
	v_mul_f32_e32 v155, v155, v15
	v_fma_f32 v140, v60, v140, v76
	v_fma_f32 v141, v61, v141, v77
	v_fma_f32 v142, v62, v142, v78
	v_fma_f32 v143, v63, v143, v79
	v_fma_f32 v144, v64, v144, v80
	v_fma_f32 v145, v65, v145, v81
	v_fma_f32 v146, v66, v146, v82
	v_fma_f32 v147, v67, v147, v83
	v_fma_f32 v148, v68, v148, v84
	v_fma_f32 v149, v69, v149, v85
	v_fma_f32 v150, v70, v150, v86
	v_fma_f32 v151, v71, v151, v87
	v_fma_f32 v152, v72, v152, v88
	v_fma_f32 v153, v73, v153, v89
	v_fma_f32 v154, v74, v154, v90
	v_fma_f32 v155, v75, v155, v91
	v_cvt_pk_bf16_f32 v16, v140, v141
	v_cvt_pk_bf16_f32 v17, v142, v143
	global_store_dwordx2 v[12:13], v[16:17], off
	v_cvt_pk_bf16_f32 v18, v144, v145
	v_cvt_pk_bf16_f32 v19, v146, v147
	global_store_dwordx2 v[12:13], v[18:19], off offset:512
	v_cvt_pk_bf16_f32 v20, v148, v149
	v_cvt_pk_bf16_f32 v21, v150, v151
	global_store_dwordx2 v[12:13], v[20:21], off offset:1024
	v_cvt_pk_bf16_f32 v22, v152, v153
	v_cvt_pk_bf16_f32 v23, v154, v155
	global_store_dwordx2 v[12:13], v[22:23], off offset:1536
	s_waitcnt vmcnt(8)
; DI unsigned pk2(float lo, float hi) { const hwf2_t v = {lo, hi}; const hwbf2_t b = __builtin_convertvector(v, hwbf2_t); return __builtin_bit_cast(unsigned, b); }
; DI void ln_pass(CP c, int mode, const float* gam, const float* bet, const float* modsc, const float* modsh, int bid, int nb, bool fin) {
;     ...
;         if (modsc) { const int mr = modrow_of(r);
; #pragma unroll
;             for (int i = 0; i < 4; ++i) { const int col = lane * 4 + 256 * i; const f32x4 sc = *(const f32x4*)(modsc + (size_t)mr * 12288 + col), sh = *(const f32x4*)(modsh + (size_t)mr * 12288 + col);
;                 const f32x4 h = v[i] * (sc + 1.0f) + sh; u32x2 w; w.x = pk2(h[0], h[1]); w.y = pk2(h[2], h[3]);
;                 *(u32x2*)(H + (size_t)r * DM + col) = w; } }
	v_add_f32_e32 v108, 1.0, v108
	v_add_f32_e32 v109, 1.0, v109
	v_add_f32_e32 v110, 1.0, v110
	v_add_f32_e32 v111, 1.0, v111
	v_add_f32_e32 v112, 1.0, v112
	v_add_f32_e32 v113, 1.0, v113
	v_add_f32_e32 v114, 1.0, v114
	v_add_f32_e32 v115, 1.0, v115
	v_add_f32_e32 v116, 1.0, v116
	v_add_f32_e32 v117, 1.0, v117
	v_add_f32_e32 v118, 1.0, v118
	v_add_f32_e32 v119, 1.0, v119
	v_add_f32_e32 v120, 1.0, v120
	v_add_f32_e32 v121, 1.0, v121
	v_add_f32_e32 v122, 1.0, v122
	v_add_f32_e32 v123, 1.0, v123
	v_fma_f32 v108, v108, v140, v124
	v_fma_f32 v109, v109, v141, v125
	v_fma_f32 v110, v110, v142, v126
	v_fma_f32 v111, v111, v143, v127
	v_fma_f32 v112, v112, v144, v128
	v_fma_f32 v113, v113, v145, v129
	v_fma_f32 v114, v114, v146, v130
	v_fma_f32 v115, v115, v147, v131
	v_fma_f32 v116, v116, v148, v132
	v_fma_f32 v117, v117, v149, v133
	v_fma_f32 v118, v118, v150, v134
	v_fma_f32 v119, v119, v151, v135
	v_fma_f32 v120, v120, v152, v136
	v_fma_f32 v121, v121, v153, v137
	v_fma_f32 v122, v122, v154, v138
	v_fma_f32 v123, v123, v155, v139
	v_cvt_pk_bf16_f32 v50, v108, v109
	v_cvt_pk_bf16_f32 v51, v110, v111
	global_store_dwordx2 v[10:11], v[50:51], off
	v_cvt_pk_bf16_f32 v52, v112, v113
	v_cvt_pk_bf16_f32 v53, v114, v115
	global_store_dwordx2 v[10:11], v[52:53], off offset:512
	v_cvt_pk_bf16_f32 v54, v116, v117
	v_cvt_pk_bf16_f32 v55, v118, v119
	global_store_dwordx2 v[10:11], v[54:55], off offset:1024
	v_cvt_pk_bf16_f32 v56, v120, v121
	v_cvt_pk_bf16_f32 v57, v122, v123
	global_store_dwordx2 v[10:11], v[56:57], off offset:1536
	v_add_u32_e32 v30, s76, v30
	v_mov_b32_e32 v12, v48
	v_mov_b32_e32 v13, v49
	v_lshl_add_u64 v[10:11], v[10:11], 0, s[44:45]
	v_cmp_lt_i32_e32 vcc, s81, v30
	s_or_b64 s[6:7], vcc, s[6:7]
	s_andn2_b64 exec, exec, s[6:7]
	s_cbranch_execz .LBB0_416
	v_add_u32_e32 v0, 0xffffc000, v30
	v_lshrrev_b32_e32 v0, 4, v0
	v_add_u32_e32 v0, 1, v0
	v_cmp_lt_i32_e32 vcc, s3, v30
	s_nop 1
	v_cndmask_b32_e32 v0, 0, v0, vcc
	v_mad_u64_u32 v[24:25], s[8:9], v0, s86, v[6:7]
	v_mad_u64_u32 v[46:47], s[8:9], v0, s86, v[8:9]
	global_load_dwordx4 v[108:111], v[24:25], off
	global_load_dwordx4 v[112:115], v[24:25], off offset:1024
	global_load_dwordx4 v[116:119], v[24:25], off offset:2048
	global_load_dwordx4 v[120:123], v[24:25], off offset:3072
	global_load_dwordx4 v[124:127], v[46:47], off
	global_load_dwordx4 v[128:131], v[46:47], off offset:1024
	global_load_dwordx4 v[132:135], v[46:47], off offset:2048
	global_load_dwordx4 v[136:139], v[46:47], off offset:3072
	s_waitcnt vmcnt(8)
; DI unsigned pk2(float lo, float hi) { const hwf2_t v = {lo, hi}; const hwbf2_t b = __builtin_convertvector(v, hwbf2_t); return __builtin_bit_cast(unsigned, b); }
; DI float lo16(unsigned w) { return __uint_as_float(w << 16); }
; DI float hi16(unsigned w) { return __uint_as_float(w & 0xffff0000u); }
; DI float wave_sum(float v) { for (int o = 32; o >= 1; o >>= 1) v += __shfl_xor(v, o); return v; }
; DI void ln_pass(CP c, int mode, const float* gam, const float* bet, const float* modsc, const float* modsh, int bid, int nb, bool fin) {
;     ...
;         else {
; #pragma unroll
;             for (int i = 0; i < 4; ++i) { const u32x2 w = *(const u32x2*)(XB + (size_t)r * DM + lane * 4 + 256 * i); v[i] = (f32x4){lo16(w.x), hi16(w.x), lo16(w.y), hi16(w.y)}; } }
;         if (mode != 1) {
;             float s = 0.f;
; #pragma unroll
;             for (int i = 0; i < 4; ++i) s += v[i][0] + v[i][1] + v[i][2] + v[i][3];
;             const float mean = wave_sum(s) * (1.f / 1024.f); float q = 0.f;
; #pragma unroll
;             for (int i = 0; i < 4; ++i) { const f32x4 d = v[i] - mean; q += d[0] * d[0] + d[1] * d[1] + d[2] * d[2] + d[3] * d[3]; }
;             const float rstd = rsqrtf(wave_sum(q) * (1.f / 1024.f) + 1e-5f);
; #pragma unroll
;             for (int i = 0; i < 4; ++i) { const int col = lane * 4 + 256 * i; const f32x4 g = *(const f32x4*)(gam + col), b = *(const f32x4*)(bet + col);
;                 v[i] = (v[i] - mean) * rstd * g + b;
;                 if (fin) *(f32x4*)(c->out + (size_t)r * DM + col) = v[i];
;                 else { u32x2 w; w.x = pk2(v[i][0], v[i][1]); w.y = pk2(v[i][2], v[i][3]); *(u32x2*)(XB + (size_t)r * DM + col) = w; } }
;         }
;         if (modsc) { const int mr = modrow_of(r);
; #pragma unroll
;             for (int i = 0; i < 4; ++i) { const int col = lane * 4 + 256 * i; const f32x4 sc = *(const f32x4*)(modsc + (size_t)mr * 12288 + col), sh = *(const f32x4*)(modsh + (size_t)mr * 12288 + col);
;                 const f32x4 h = v[i] * (sc + 1.0f) + sh; u32x2 w; w.x = pk2(h[0], h[1]); w.y = pk2(h[2], h[3]);
;                 *(u32x2*)(H + (size_t)r * DM + col) = w; } }
	v_lshl_add_u64 v[48:49], v[12:13], 0, s[44:45]
	global_load_dwordx2 v[92:93], v[48:49], off
	global_load_dwordx2 v[94:95], v[48:49], off offset:512
	global_load_dwordx2 v[96:97], v[48:49], off offset:1024
	global_load_dwordx2 v[98:99], v[48:49], off offset:1536
	v_lshlrev_b32_e32 v140, 16, v100
	v_and_b32_e32 v141, 0xffff0000, v100
	v_lshlrev_b32_e32 v142, 16, v101
	v_and_b32_e32 v143, 0xffff0000, v101
	v_lshlrev_b32_e32 v144, 16, v102
	v_and_b32_e32 v145, 0xffff0000, v102
	v_lshlrev_b32_e32 v146, 16, v103
	v_and_b32_e32 v147, 0xffff0000, v103
	v_lshlrev_b32_e32 v148, 16, v104
	v_and_b32_e32 v149, 0xffff0000, v104
	v_lshlrev_b32_e32 v150, 16, v105
	v_and_b32_e32 v151, 0xffff0000, v105
	v_lshlrev_b32_e32 v152, 16, v106
	v_and_b32_e32 v153, 0xffff0000, v106
	v_lshlrev_b32_e32 v154, 16, v107
	v_and_b32_e32 v155, 0xffff0000, v107
	v_add_f32_e32 v0, v140, v141
	v_add_f32_e32 v0, v0, v142
	v_add_f32_e32 v0, v0, v143
	v_add_f32_e32 v0, v0, v144
	v_add_f32_e32 v0, v0, v145
	v_add_f32_e32 v0, v0, v146
	v_add_f32_e32 v0, v0, v147
	v_add_f32_e32 v0, v0, v148
	v_add_f32_e32 v0, v0, v149
	v_add_f32_e32 v0, v0, v150
	v_add_f32_e32 v0, v0, v151
	v_add_f32_e32 v0, v0, v152
	v_add_f32_e32 v0, v0, v153
	v_add_f32_e32 v0, v0, v154
	v_add_f32_e32 v0, v0, v155
	s_nop 1
	v_add_f32_dpp v0, v0, v0 row_shr:1 row_mask:0xf bank_mask:0xf bound_ctrl:0
	s_nop 1
	v_add_f32_dpp v0, v0, v0 row_shr:2 row_mask:0xf bank_mask:0xf bound_ctrl:0
	s_nop 1
	v_add_f32_dpp v0, v0, v0 row_shr:4 row_mask:0xf bank_mask:0xf bound_ctrl:0
	s_nop 1
	v_add_f32_dpp v0, v0, v0 row_shr:8 row_mask:0xf bank_mask:0xf bound_ctrl:0
	s_nop 1
	v_add_f32_dpp v0, v0, v0 row_bcast:15 row_mask:0xa bank_mask:0xf
	s_nop 1
	v_add_f32_dpp v0, v0, v0 row_bcast:31 row_mask:0xc bank_mask:0xf
	s_nop 1
	v_readlane_b32 vcc_lo, v0, 63
	s_nop 1
	v_mov_b32_e32 v0, vcc_lo
	v_fmac_f32_e32 v140, 0xba800000, v0
	v_fmac_f32_e32 v141, 0xba800000, v0
	v_fmac_f32_e32 v142, 0xba800000, v0
	v_fmac_f32_e32 v143, 0xba800000, v0
	v_fmac_f32_e32 v144, 0xba800000, v0
	v_fmac_f32_e32 v145, 0xba800000, v0
	v_fmac_f32_e32 v146, 0xba800000, v0
	v_fmac_f32_e32 v147, 0xba800000, v0
	v_fmac_f32_e32 v148, 0xba800000, v0
	v_fmac_f32_e32 v149, 0xba800000, v0
	v_fmac_f32_e32 v150, 0xba800000, v0
	v_fmac_f32_e32 v151, 0xba800000, v0
	v_fmac_f32_e32 v152, 0xba800000, v0
	v_fmac_f32_e32 v153, 0xba800000, v0
	v_fmac_f32_e32 v154, 0xba800000, v0
	v_fmac_f32_e32 v155, 0xba800000, v0
	v_mul_f32_e32 v15, v140, v140
	v_fmac_f32_e32 v15, v141, v141
	v_fmac_f32_e32 v15, v142, v142
	v_fmac_f32_e32 v15, v143, v143
	v_fmac_f32_e32 v15, v144, v144
	v_fmac_f32_e32 v15, v145, v145
	v_fmac_f32_e32 v15, v146, v146
	v_fmac_f32_e32 v15, v147, v147
	v_fmac_f32_e32 v15, v148, v148
	v_fmac_f32_e32 v15, v149, v149
	v_fmac_f32_e32 v15, v150, v150
	v_fmac_f32_e32 v15, v151, v151
	v_fmac_f32_e32 v15, v152, v152
	v_fmac_f32_e32 v15, v153, v153
	v_fmac_f32_e32 v15, v154, v154
	v_fmac_f32_e32 v15, v155, v155
	s_nop 1
	v_add_f32_dpp v15, v15, v15 row_shr:1 row_mask:0xf bank_mask:0xf bound_ctrl:0
	s_nop 1
	v_add_f32_dpp v15, v15, v15 row_shr:2 row_mask:0xf bank_mask:0xf bound_ctrl:0
	s_nop 1
	v_add_f32_dpp v15, v15, v15 row_shr:4 row_mask:0xf bank_mask:0xf bound_ctrl:0
	s_nop 1
	v_add_f32_dpp v15, v15, v15 row_shr:8 row_mask:0xf bank_mask:0xf bound_ctrl:0
	s_nop 1
	v_add_f32_dpp v15, v15, v15 row_bcast:15 row_mask:0xa bank_mask:0xf
	s_nop 1
	v_add_f32_dpp v15, v15, v15 row_bcast:31 row_mask:0xc bank_mask:0xf
	s_nop 1
	v_readlane_b32 vcc_lo, v15, 63
	s_nop 1
	v_mov_b32_e32 v15, vcc_lo
	v_fmamk_f32 v15, v15, 0x3a800000, v189
	v_rsq_f32_e32 v15, v15
	s_nop 0
	v_mul_f32_e32 v140, v140, v15
	v_mul_f32_e32 v141, v141, v15
	v_mul_f32_e32 v142, v142, v15
	v_mul_f32_e32 v143, v143, v15
	v_mul_f32_e32 v144, v144, v15
	v_mul_f32_e32 v145, v145, v15
	v_mul_f32_e32 v146, v146, v15
	v_mul_f32_e32 v147, v147, v15
	v_mul_f32_e32 v148, v148, v15
	v_mul_f32_e32 v149, v149, v15
	v_mul_f32_e32 v150, v150, v15
	v_mul_f32_e32 v151, v151, v15
	v_mul_f32_e32 v152, v152, v15
	v_mul_f32_e32 v153, v153, v15
	v_mul_f32_e32 v154, v154, v15
	v_mul_f32_e32 v155, v155, v15
	v_fma_f32 v140, v60, v140, v76
	v_fma_f32 v141, v61, v141, v77
	v_fma_f32 v142, v62, v142, v78
	v_fma_f32 v143, v63, v143, v79
	v_fma_f32 v144, v64, v144, v80
	v_fma_f32 v145, v65, v145, v81
	v_fma_f32 v146, v66, v146, v82
	v_fma_f32 v147, v67, v147, v83
	v_fma_f32 v148, v68, v148, v84
	v_fma_f32 v149, v69, v149, v85
	v_fma_f32 v150, v70, v150, v86
	v_fma_f32 v151, v71, v151, v87
	v_fma_f32 v152, v72, v152, v88
	v_fma_f32 v153, v73, v153, v89
	v_fma_f32 v154, v74, v154, v90
	v_fma_f32 v155, v75, v155, v91
	v_cvt_pk_bf16_f32 v16, v140, v141
	v_cvt_pk_bf16_f32 v17, v142, v143
	global_store_dwordx2 v[12:13], v[16:17], off
	v_cvt_pk_bf16_f32 v18, v144, v145
	v_cvt_pk_bf16_f32 v19, v146, v147
	global_store_dwordx2 v[12:13], v[18:19], off offset:512
	v_cvt_pk_bf16_f32 v20, v148, v149
	v_cvt_pk_bf16_f32 v21, v150, v151
	global_store_dwordx2 v[12:13], v[20:21], off offset:1024
	v_cvt_pk_bf16_f32 v22, v152, v153
	v_cvt_pk_bf16_f32 v23, v154, v155
	global_store_dwordx2 v[12:13], v[22:23], off offset:1536
	s_waitcnt vmcnt(8)
	v_add_f32_e32 v108, 1.0, v108
	v_add_f32_e32 v109, 1.0, v109
	v_add_f32_e32 v110, 1.0, v110
	v_add_f32_e32 v111, 1.0, v111
	v_add_f32_e32 v112, 1.0, v112
	v_add_f32_e32 v113, 1.0, v113
	v_add_f32_e32 v114, 1.0, v114
	v_add_f32_e32 v115, 1.0, v115
	v_add_f32_e32 v116, 1.0, v116
	v_add_f32_e32 v117, 1.0, v117
	v_add_f32_e32 v118, 1.0, v118
	v_add_f32_e32 v119, 1.0, v119
	v_add_f32_e32 v120, 1.0, v120
	v_add_f32_e32 v121, 1.0, v121
	v_add_f32_e32 v122, 1.0, v122
	v_add_f32_e32 v123, 1.0, v123
	v_fma_f32 v108, v108, v140, v124
	v_fma_f32 v109, v109, v141, v125
	v_fma_f32 v110, v110, v142, v126
	v_fma_f32 v111, v111, v143, v127
	v_fma_f32 v112, v112, v144, v128
	v_fma_f32 v113, v113, v145, v129
	v_fma_f32 v114, v114, v146, v130
	v_fma_f32 v115, v115, v147, v131
	v_fma_f32 v116, v116, v148, v132
	v_fma_f32 v117, v117, v149, v133
	v_fma_f32 v118, v118, v150, v134
	v_fma_f32 v119, v119, v151, v135
	v_fma_f32 v120, v120, v152, v136
	v_fma_f32 v121, v121, v153, v137
	v_fma_f32 v122, v122, v154, v138
	v_fma_f32 v123, v123, v155, v139
	v_cvt_pk_bf16_f32 v50, v108, v109
	v_cvt_pk_bf16_f32 v51, v110, v111
	global_store_dwordx2 v[10:11], v[50:51], off
	v_cvt_pk_bf16_f32 v52, v112, v113
	v_cvt_pk_bf16_f32 v53, v114, v115
	global_store_dwordx2 v[10:11], v[52:53], off offset:512
	v_cvt_pk_bf16_f32 v54, v116, v117
	v_cvt_pk_bf16_f32 v55, v118, v119
	global_store_dwordx2 v[10:11], v[54:55], off offset:1024
	v_cvt_pk_bf16_f32 v56, v120, v121
	v_cvt_pk_bf16_f32 v57, v122, v123
	global_store_dwordx2 v[10:11], v[56:57], off offset:1536
	v_add_u32_e32 v30, s76, v30
	v_mov_b32_e32 v12, v48
	v_mov_b32_e32 v13, v49
	v_lshl_add_u64 v[10:11], v[10:11], 0, s[44:45]
	v_cmp_lt_i32_e32 vcc, s81, v30
	s_or_b64 s[6:7], vcc, s[6:7]
	s_andn2_b64 exec, exec, s[6:7]
	s_cbranch_execnz .LBB0_415
